# grid barrier two-level with 8 groups of 32 (blockIdx&7) instead of 4 groups of 64
# baseline (speedup 1.0000x reference)
; DI void fast_grid_barrier(unsigned* ctr, unsigned target) {
;     asm volatile("s_waitcnt vmcnt(0)" ::: "memory");
;     __syncthreads();
;     if (threadIdx.x == 0) {
;         __builtin_amdgcn_fence(__ATOMIC_RELEASE, "agent");
;         asm volatile("s_waitcnt vmcnt(0)" ::: "memory");
;         __hip_atomic_fetch_add(ctr, 1u, __ATOMIC_RELAXED, __HIP_MEMORY_SCOPE_AGENT);
;         while (__hip_atomic_load(ctr, __ATOMIC_RELAXED, __HIP_MEMORY_SCOPE_AGENT) < target) __builtin_amdgcn_s_sleep(1);
;         __builtin_amdgcn_fence(__ATOMIC_ACQUIRE, "agent");
;         asm volatile("s_waitcnt vmcnt(0)" ::: "memory");
;     }
;     __syncthreads();
; }
.LBB0_4:
	s_cmp_le_i32 s70, s12
	s_cbranch_scc1 .LBB0_26
	v_readlane_b32 s0, v255, 4
	s_cmp_lg_u32 s70, s0
	s_mov_b64 s[0:1], -1
	s_waitcnt vmcnt(0)
	v_readlane_b32 s0, v255, 11
	s_add_i32 s4, s0, 1
	s_barrier
	s_mov_b64 s[0:1], exec
	v_readlane_b32 s6, v255, 12
	v_readlane_b32 s7, v255, 13
	s_and_b64 s[6:7], s[0:1], s[6:7]
	s_mov_b64 exec, s[6:7]
	s_cbranch_execz .LBB0_12
	buffer_wbl2 sc1
	s_waitcnt vmcnt(0)
	s_and_b32 s5, s2, 7
	s_lshl_b32 s8, s5, 5
	s_cmp_eq_u32 s5, 0
	s_cselect_b32 s8, 16, s8
	v_mov_b32_e32 v0, 1
	v_mov_b32_e32 v1, s8
	global_atomic_add v2, v1, v0, s[14:15] sc0
	s_sub_i32 s9, s72, s5
	s_add_i32 s9, s9, 7
	s_lshr_b32 s9, s9, 3
	s_mul_i32 s9, s9, s4
	s_lshl_b32 s5, s4, 3
	s_waitcnt vmcnt(0)
	v_add_u32_e32 v2, 1, v2
	v_cmp_eq_u32_e32 vcc, s9, v2
	s_cbranch_vccz .Lgb_poll
	global_atomic_add v165, v0, s[14:15]
